# softmax row max and row sum as four independent chains (same instruction count, shorter dependency chains)
# baseline (speedup 1.0000x reference)
; #define LAS __attribute__((address_space(3)))
; #define LDS_WAIT() asm volatile("s_waitcnt lgkmcnt(0)" ::: "memory")
; __device__ __forceinline__ void kv8_pv(const u32x4 (&buf)[8], f32x2v (&o2)[8], const LAS float* srow, int b) {
;     const LAS f32x4* p4 = (const LAS f32x4*)(srow + b * 8);
;     const f32x4 p0 = p4[0], p1 = p4[1];
;     const float p[8] = {p0.x, p0.y, p0.z, p0.w, p1.x, p1.y, p1.z, p1.w};
; #pragma unroll
;     for (int u = 0; u < 8; ++u) {
;         const u32x4 v = buf[u]; const f32x2v pp = {p[u], p[u]};
;         o2[0] = __builtin_elementwise_fma(pp, __builtin_amdgcn_cvt_pk_f32_fp8(v.x, false), o2[0]); o2[1] = __builtin_elementwise_fma(pp, __builtin_amdgcn_cvt_pk_f32_fp8(v.x, true), o2[1]);
;         o2[2] = __builtin_elementwise_fma(pp, __builtin_amdgcn_cvt_pk_f32_fp8(v.y, false), o2[2]); o2[3] = __builtin_elementwise_fma(pp, __builtin_amdgcn_cvt_pk_f32_fp8(v.y, true), o2[3]);
;         o2[4] = __builtin_elementwise_fma(pp, __builtin_amdgcn_cvt_pk_f32_fp8(v.z, false), o2[4]); o2[5] = __builtin_elementwise_fma(pp, __builtin_amdgcn_cvt_pk_f32_fp8(v.z, true), o2[5]);
;         o2[6] = __builtin_elementwise_fma(pp, __builtin_amdgcn_cvt_pk_f32_fp8(v.w, false), o2[6]); o2[7] = __builtin_elementwise_fma(pp, __builtin_amdgcn_cvt_pk_f32_fp8(v.w, true), o2[7]);
;     }
; __device__ __forceinline__ void attn_query8(const unsigned char* __restrict__ KV8, const bf16_t* __restrict__ Z, const int* __restrict__ SEL, bf16_t* __restrict__ YMIX, int t, LAS float* sbuf  ) {
;     ...
;     for (int h = 0; h < 8; ++h) {
;         float sv[4]; float mx = -__builtin_inff();
; #pragma unroll
;         for (int jj = 0; jj < 4; ++jj) { const int j = lane + 64 * jj; const float s = sbuf[h * 256 + j]; sv[jj] = (j < nsel) ? s : -__builtin_inff(); mx = fmaxf(mx, sv[jj]); }
;         mx = wave_max(mx); float sm = 0.f;
; #pragma unroll
;         for (int jj = 0; jj < 4; ++jj) { const int j = lane + 64 * jj; sv[jj] = (j < nsel) ? __expf(sv[jj] - mx) : 0.f; sm += sv[jj]; }
;         sm = wave_sum(sm); const float inv = 1.f / sm;
; #pragma unroll
;         for (int jj = 0; jj < 4; ++jj) sbuf[h * 256 + lane + 64 * jj] = sv[jj] * inv;
;     }
;     LDS_WAIT();
.Latt_nomask:
	v_max3_f32 v134, v150, v151, v152
	v_max3_f32 v135, v153, v154, v155
	v_max3_f32 v136, v156, v157, v158
	v_max3_f32 v137, v159, v160, v161
	v_max3_f32 v134, v134, v162, v163
	v_max3_f32 v135, v135, v164, v165
	v_max3_f32 v136, v136, v166, v167
	v_max3_f32 v137, v137, v168, v169
	v_max3_f32 v134, v134, v170, v171
	v_max3_f32 v135, v135, v172, v173
	v_max3_f32 v136, v136, v174, v175
	v_max3_f32 v137, v137, v176, v177
	v_max3_f32 v134, v134, v178, v179
	v_max3_f32 v135, v135, v180, v181
	v_max3_f32 v134, v134, v135, v136
	v_max_f32_e32 v134, v134, v137
	s_nop 1
	v_mov_b32_dpp v135, v134 row_ror:8 row_mask:0xf bank_mask:0xf
	s_nop 0
	v_max_f32_e32 v134, v134, v135
	v_mov_b32_e32 v135, v134
	s_nop 1
	v_permlane16_swap_b32_e32 v134, v135
	v_max_f32_e32 v134, v134, v135
	v_mov_b32_e32 v135, v134
	s_nop 1
	v_permlane32_swap_b32_e32 v134, v135
	v_max_f32_e32 v134, v134, v135
	v_mul_f32_e32 v134, 0xbfb8aa3b, v134
	v_fma_f32 v150, v150, s28, v134
	v_fma_f32 v151, v151, s28, v134
	v_fma_f32 v152, v152, s28, v134
	v_fma_f32 v153, v153, s28, v134
	v_fma_f32 v154, v154, s28, v134
	v_fma_f32 v155, v155, s28, v134
	v_fma_f32 v156, v156, s28, v134
	v_fma_f32 v157, v157, s28, v134
	v_fma_f32 v158, v158, s28, v134
	v_fma_f32 v159, v159, s28, v134
	v_fma_f32 v160, v160, s28, v134
	v_fma_f32 v161, v161, s28, v134
	v_fma_f32 v162, v162, s28, v134
	v_fma_f32 v163, v163, s28, v134
	v_fma_f32 v164, v164, s28, v134
	v_fma_f32 v165, v165, s28, v134
	v_fma_f32 v166, v166, s28, v134
	v_fma_f32 v167, v167, s28, v134
	v_fma_f32 v168, v168, s28, v134
	v_fma_f32 v169, v169, s28, v134
	v_fma_f32 v170, v170, s28, v134
	v_fma_f32 v171, v171, s28, v134
	v_fma_f32 v172, v172, s28, v134
	v_fma_f32 v173, v173, s28, v134
	v_fma_f32 v174, v174, s28, v134
	v_fma_f32 v175, v175, s28, v134
	v_fma_f32 v176, v176, s28, v134
	v_fma_f32 v177, v177, s28, v134
	v_fma_f32 v178, v178, s28, v134
	v_fma_f32 v179, v179, s28, v134
	v_fma_f32 v180, v180, s28, v134
	v_fma_f32 v181, v181, s28, v134
	v_exp_f32_e32 v150, v150
	v_exp_f32_e32 v151, v151
	v_exp_f32_e32 v152, v152
	v_exp_f32_e32 v153, v153
	v_exp_f32_e32 v154, v154
	v_exp_f32_e32 v155, v155
	v_exp_f32_e32 v156, v156
	v_exp_f32_e32 v157, v157
	v_exp_f32_e32 v158, v158
	v_exp_f32_e32 v159, v159
	v_exp_f32_e32 v160, v160
	v_exp_f32_e32 v161, v161
	v_exp_f32_e32 v162, v162
	v_exp_f32_e32 v163, v163
	v_exp_f32_e32 v164, v164
	v_exp_f32_e32 v165, v165
	v_exp_f32_e32 v166, v166
	v_exp_f32_e32 v167, v167
	v_exp_f32_e32 v168, v168
	v_exp_f32_e32 v169, v169
	v_exp_f32_e32 v170, v170
	v_exp_f32_e32 v171, v171
	v_exp_f32_e32 v172, v172
	v_exp_f32_e32 v173, v173
	v_exp_f32_e32 v174, v174
	v_exp_f32_e32 v175, v175
	v_exp_f32_e32 v176, v176
	v_exp_f32_e32 v177, v177
	v_exp_f32_e32 v178, v178
	v_exp_f32_e32 v179, v179
	v_exp_f32_e32 v180, v180
	v_exp_f32_e32 v181, v181
	s_nop 0
	v_add_f32_e32 v134, v150, v151
	v_add_f32_e32 v135, v152, v153
	v_add_f32_e32 v136, v154, v155
	v_add_f32_e32 v137, v156, v157
	v_add_f32_e32 v134, v134, v158
	v_add_f32_e32 v135, v135, v159
	v_add_f32_e32 v136, v136, v160
	v_add_f32_e32 v137, v137, v161
	v_add_f32_e32 v134, v134, v162
	v_add_f32_e32 v135, v135, v163
	v_add_f32_e32 v136, v136, v164
	v_add_f32_e32 v137, v137, v165
	v_add_f32_e32 v134, v134, v166
	v_add_f32_e32 v135, v135, v167
	v_add_f32_e32 v136, v136, v168
	v_add_f32_e32 v137, v137, v169
	v_add_f32_e32 v134, v134, v170
	v_add_f32_e32 v135, v135, v171
	v_add_f32_e32 v136, v136, v172
	v_add_f32_e32 v137, v137, v173
	v_add_f32_e32 v134, v134, v174
	v_add_f32_e32 v135, v135, v175
	v_add_f32_e32 v136, v136, v176
	v_add_f32_e32 v137, v137, v177
	v_add_f32_e32 v134, v134, v178
	v_add_f32_e32 v135, v135, v179
	v_add_f32_e32 v136, v136, v180
	v_add_f32_e32 v137, v137, v181
	v_add_f32_e32 v134, v134, v135
	v_add_f32_e32 v136, v136, v137
	v_add_f32_e32 v134, v134, v136
	s_nop 1
	v_mov_b32_dpp v135, v134 row_ror:8 row_mask:0xf bank_mask:0xf
	s_nop 0
	v_add_f32_e32 v134, v134, v135
	v_mov_b32_e32 v135, v134
	s_nop 1
	v_permlane16_swap_b32_e32 v134, v135
	v_add_f32_e32 v134, v134, v135
	v_mov_b32_e32 v135, v134
	s_nop 1
	v_permlane32_swap_b32_e32 v134, v135
	v_add_f32_e32 v134, v134, v135
	v_div_scale_f32 v132, s[8:9], v134, v134, 1.0
	v_rcp_f32_e32 v135, v132
	v_div_scale_f32 v133, vcc, 1.0, v134, 1.0
	v_fma_f32 v136, -v132, v135, 1.0
	v_fmac_f32_e32 v135, v136, v135
	v_mul_f32_e32 v136, v133, v135
	v_fma_f32 v137, -v132, v136, v133
	v_fmac_f32_e32 v136, v137, v135
	v_fma_f32 v132, -v132, v136, v133
	s_nop 1
	v_div_fmas_f32 v132, v132, v135, v136
	v_div_fixup_f32 v134, v132, v134, 1.0
	v_mov_b32_e32 v149, v134
	s_waitcnt vmcnt(31)
	ds_write_b32 v148, v240 offset:0
	ds_write_b32 v148, v241 offset:32
	ds_write_b32 v148, v242 offset:64
	ds_write_b32 v148, v243 offset:96
	v_cvt_pk_f32_fp8_e32 v[214:215], v0
	v_cvt_pk_f32_fp8_sdwa v[216:217], v0 src0_sel:WORD_1
	v_pk_mul_f32 v[198:199], v[150:151], v[214:215] op_sel_hi:[0,1]
	v_pk_mul_f32 v[200:201], v[150:151], v[216:217] op_sel_hi:[0,1]
	v_cvt_pk_f32_fp8_e32 v[218:219], v1
	v_cvt_pk_f32_fp8_sdwa v[220:221], v1 src0_sel:WORD_1
	v_pk_mul_f32 v[202:203], v[150:151], v[218:219] op_sel_hi:[0,1]
	v_pk_mul_f32 v[204:205], v[150:151], v[220:221] op_sel_hi:[0,1]
	v_cvt_pk_f32_fp8_e32 v[214:215], v2
	v_cvt_pk_f32_fp8_sdwa v[216:217], v2 src0_sel:WORD_1
	v_pk_mul_f32 v[206:207], v[150:151], v[214:215] op_sel_hi:[0,1]
	v_pk_mul_f32 v[208:209], v[150:151], v[216:217] op_sel_hi:[0,1]
	v_cvt_pk_f32_fp8_e32 v[218:219], v3
	v_cvt_pk_f32_fp8_sdwa v[220:221], v3 src0_sel:WORD_1
	v_pk_mul_f32 v[210:211], v[150:151], v[218:219] op_sel_hi:[0,1]
	v_pk_mul_f32 v[212:213], v[150:151], v[220:221] op_sel_hi:[0,1]
	s_waitcnt vmcnt(30)
; #define LAS __attribute__((address_space(3)))
; __device__ __forceinline__ void kv8_issue(u32x4 (&buf)[8], __amdgpu_buffer_rsrc_t rs, int voff  , int sbase  , const int (&iv)[4], int b) {
;     const int jj = b >> 3, l0 = (b & 7) * 8;
;     const int ivb = (jj == 0) ? iv[0] : (jj == 1) ? iv[1] : (jj == 2) ? iv[2] : iv[3];
; #pragma unroll
;     for (int u = 0; u < 8; ++u) { const int si = __builtin_amdgcn_readlane(ivb, l0 + u); buf[u] = __builtin_amdgcn_raw_buffer_load_b128(rs, voff, si * 2048 + sbase, KV8_AUX); }
; }
; __device__ __forceinline__ void kv8_pv(const u32x4 (&buf)[8], f32x2v (&o2)[8], const LAS float* srow, int b) {
;     const LAS f32x4* p4 = (const LAS f32x4*)(srow + b * 8);
;     const f32x4 p0 = p4[0], p1 = p4[1];
;     const float p[8] = {p0.x, p0.y, p0.z, p0.w, p1.x, p1.y, p1.z, p1.w};
; #pragma unroll
;     for (int u = 0; u < 8; ++u) {
;         const u32x4 v = buf[u]; const f32x2v pp = {p[u], p[u]};
;         o2[0] = __builtin_elementwise_fma(pp, __builtin_amdgcn_cvt_pk_f32_fp8(v.x, false), o2[0]); o2[1] = __builtin_elementwise_fma(pp, __builtin_amdgcn_cvt_pk_f32_fp8(v.x, true), o2[1]);
;         o2[2] = __builtin_elementwise_fma(pp, __builtin_amdgcn_cvt_pk_f32_fp8(v.y, false), o2[2]); o2[3] = __builtin_elementwise_fma(pp, __builtin_amdgcn_cvt_pk_f32_fp8(v.y, true), o2[3]);
;         o2[4] = __builtin_elementwise_fma(pp, __builtin_amdgcn_cvt_pk_f32_fp8(v.z, false), o2[4]); o2[5] = __builtin_elementwise_fma(pp, __builtin_amdgcn_cvt_pk_f32_fp8(v.z, true), o2[5]);
;         o2[6] = __builtin_elementwise_fma(pp, __builtin_amdgcn_cvt_pk_f32_fp8(v.w, false), o2[6]); o2[7] = __builtin_elementwise_fma(pp, __builtin_amdgcn_cvt_pk_f32_fp8(v.w, true), o2[7]);
;     }
	v_cvt_pk_f32_fp8_e32 v[214:215], v4
	v_cvt_pk_f32_fp8_sdwa v[216:217], v4 src0_sel:WORD_1
	v_pk_fma_f32 v[198:199], v[150:151], v[214:215], v[198:199] op_sel:[1,0,0]
	v_pk_fma_f32 v[200:201], v[150:151], v[216:217], v[200:201] op_sel:[1,0,0]
	v_cvt_pk_f32_fp8_e32 v[218:219], v5
	v_cvt_pk_f32_fp8_sdwa v[220:221], v5 src0_sel:WORD_1
	v_pk_fma_f32 v[202:203], v[150:151], v[218:219], v[202:203] op_sel:[1,0,0]
	v_pk_fma_f32 v[204:205], v[150:151], v[220:221], v[204:205] op_sel:[1,0,0]
	v_cvt_pk_f32_fp8_e32 v[214:215], v6
	v_cvt_pk_f32_fp8_sdwa v[216:217], v6 src0_sel:WORD_1
	v_pk_fma_f32 v[206:207], v[150:151], v[214:215], v[206:207] op_sel:[1,0,0]
	v_pk_fma_f32 v[208:209], v[150:151], v[216:217], v[208:209] op_sel:[1,0,0]
	v_cvt_pk_f32_fp8_e32 v[218:219], v7
	v_cvt_pk_f32_fp8_sdwa v[220:221], v7 src0_sel:WORD_1
	v_pk_fma_f32 v[210:211], v[150:151], v[218:219], v[210:211] op_sel:[1,0,0]
	v_pk_fma_f32 v[212:213], v[150:151], v[220:221], v[212:213] op_sel:[1,0,0]
	s_waitcnt vmcnt(29)
	v_cvt_pk_f32_fp8_e32 v[214:215], v8
	v_cvt_pk_f32_fp8_sdwa v[216:217], v8 src0_sel:WORD_1
	v_pk_fma_f32 v[198:199], v[152:153], v[214:215], v[198:199] op_sel_hi:[0,1,1]
	v_pk_fma_f32 v[200:201], v[152:153], v[216:217], v[200:201] op_sel_hi:[0,1,1]
	v_cvt_pk_f32_fp8_e32 v[218:219], v9
	v_cvt_pk_f32_fp8_sdwa v[220:221], v9 src0_sel:WORD_1
	v_pk_fma_f32 v[202:203], v[152:153], v[218:219], v[202:203] op_sel_hi:[0,1,1]
	v_pk_fma_f32 v[204:205], v[152:153], v[220:221], v[204:205] op_sel_hi:[0,1,1]
	v_cvt_pk_f32_fp8_e32 v[214:215], v10
	v_cvt_pk_f32_fp8_sdwa v[216:217], v10 src0_sel:WORD_1
	v_pk_fma_f32 v[206:207], v[152:153], v[214:215], v[206:207] op_sel_hi:[0,1,1]
	v_pk_fma_f32 v[208:209], v[152:153], v[216:217], v[208:209] op_sel_hi:[0,1,1]
	v_cvt_pk_f32_fp8_e32 v[218:219], v11
	v_cvt_pk_f32_fp8_sdwa v[220:221], v11 src0_sel:WORD_1
	v_pk_fma_f32 v[210:211], v[152:153], v[218:219], v[210:211] op_sel_hi:[0,1,1]
	v_pk_fma_f32 v[212:213], v[152:153], v[220:221], v[212:213] op_sel_hi:[0,1,1]
	s_waitcnt vmcnt(28)
	v_cvt_pk_f32_fp8_e32 v[214:215], v12
	v_cvt_pk_f32_fp8_sdwa v[216:217], v12 src0_sel:WORD_1
	v_pk_fma_f32 v[198:199], v[152:153], v[214:215], v[198:199] op_sel:[1,0,0]
	v_pk_fma_f32 v[200:201], v[152:153], v[216:217], v[200:201] op_sel:[1,0,0]
	v_cvt_pk_f32_fp8_e32 v[218:219], v13
	v_cvt_pk_f32_fp8_sdwa v[220:221], v13 src0_sel:WORD_1
	v_pk_fma_f32 v[202:203], v[152:153], v[218:219], v[202:203] op_sel:[1,0,0]
	v_pk_fma_f32 v[204:205], v[152:153], v[220:221], v[204:205] op_sel:[1,0,0]
	v_cvt_pk_f32_fp8_e32 v[214:215], v14
	v_cvt_pk_f32_fp8_sdwa v[216:217], v14 src0_sel:WORD_1
	v_pk_fma_f32 v[206:207], v[152:153], v[214:215], v[206:207] op_sel:[1,0,0]
	v_pk_fma_f32 v[208:209], v[152:153], v[216:217], v[208:209] op_sel:[1,0,0]
	v_cvt_pk_f32_fp8_e32 v[218:219], v15
	v_cvt_pk_f32_fp8_sdwa v[220:221], v15 src0_sel:WORD_1
	v_pk_fma_f32 v[210:211], v[152:153], v[218:219], v[210:211] op_sel:[1,0,0]
	v_pk_fma_f32 v[212:213], v[152:153], v[220:221], v[212:213] op_sel:[1,0,0]
	ds_read_b128 v[150:153], v139 offset:0
	s_waitcnt vmcnt(27)
	v_cvt_pk_f32_fp8_e32 v[214:215], v16
	v_cvt_pk_f32_fp8_sdwa v[216:217], v16 src0_sel:WORD_1
	v_pk_fma_f32 v[198:199], v[154:155], v[214:215], v[198:199] op_sel_hi:[0,1,1]
	v_pk_fma_f32 v[200:201], v[154:155], v[216:217], v[200:201] op_sel_hi:[0,1,1]
	v_cvt_pk_f32_fp8_e32 v[218:219], v17
	v_cvt_pk_f32_fp8_sdwa v[220:221], v17 src0_sel:WORD_1
	v_pk_fma_f32 v[202:203], v[154:155], v[218:219], v[202:203] op_sel_hi:[0,1,1]
	v_pk_fma_f32 v[204:205], v[154:155], v[220:221], v[204:205] op_sel_hi:[0,1,1]
	v_cvt_pk_f32_fp8_e32 v[214:215], v18
	v_cvt_pk_f32_fp8_sdwa v[216:217], v18 src0_sel:WORD_1
	v_pk_fma_f32 v[206:207], v[154:155], v[214:215], v[206:207] op_sel_hi:[0,1,1]
	v_pk_fma_f32 v[208:209], v[154:155], v[216:217], v[208:209] op_sel_hi:[0,1,1]
	v_cvt_pk_f32_fp8_e32 v[218:219], v19
	v_cvt_pk_f32_fp8_sdwa v[220:221], v19 src0_sel:WORD_1
	v_pk_fma_f32 v[210:211], v[154:155], v[218:219], v[210:211] op_sel_hi:[0,1,1]
	v_pk_fma_f32 v[212:213], v[154:155], v[220:221], v[212:213] op_sel_hi:[0,1,1]
	s_waitcnt vmcnt(26)
	v_cvt_pk_f32_fp8_e32 v[214:215], v20
	v_cvt_pk_f32_fp8_sdwa v[216:217], v20 src0_sel:WORD_1
	v_pk_fma_f32 v[198:199], v[154:155], v[214:215], v[198:199] op_sel:[1,0,0]
	v_pk_fma_f32 v[200:201], v[154:155], v[216:217], v[200:201] op_sel:[1,0,0]
	v_cvt_pk_f32_fp8_e32 v[218:219], v21
	v_cvt_pk_f32_fp8_sdwa v[220:221], v21 src0_sel:WORD_1
	v_pk_fma_f32 v[202:203], v[154:155], v[218:219], v[202:203] op_sel:[1,0,0]
	v_pk_fma_f32 v[204:205], v[154:155], v[220:221], v[204:205] op_sel:[1,0,0]
	v_cvt_pk_f32_fp8_e32 v[214:215], v22
	v_cvt_pk_f32_fp8_sdwa v[216:217], v22 src0_sel:WORD_1
	v_pk_fma_f32 v[206:207], v[154:155], v[214:215], v[206:207] op_sel:[1,0,0]
	v_pk_fma_f32 v[208:209], v[154:155], v[216:217], v[208:209] op_sel:[1,0,0]
	v_cvt_pk_f32_fp8_e32 v[218:219], v23
	v_cvt_pk_f32_fp8_sdwa v[220:221], v23 src0_sel:WORD_1
	v_pk_fma_f32 v[210:211], v[154:155], v[218:219], v[210:211] op_sel:[1,0,0]
	v_pk_fma_f32 v[212:213], v[154:155], v[220:221], v[212:213] op_sel:[1,0,0]
	s_waitcnt lgkmcnt(0)
	v_lshl_add_u32 v150, v150, 8, v138
	v_lshl_add_u32 v151, v151, 8, v138
	v_lshl_add_u32 v152, v152, 8, v138
	v_lshl_add_u32 v153, v153, 8, v138
	buffer_load_dwordx4 v[0:3], v150, s[16:19], s26 offen
	buffer_load_dwordx4 v[4:7], v151, s[16:19], s26 offen
	buffer_load_dwordx4 v[8:11], v152, s[16:19], s26 offen
	buffer_load_dwordx4 v[12:15], v153, s[16:19], s26 offen
	s_waitcnt vmcnt(29)
; #define LAS __attribute__((address_space(3)))
; __device__ __forceinline__ void kv8_issue(u32x4 (&buf)[8], __amdgpu_buffer_rsrc_t rs, int voff  , int sbase  , const int (&iv)[4], int b) {
;     const int jj = b >> 3, l0 = (b & 7) * 8;
;     const int ivb = (jj == 0) ? iv[0] : (jj == 1) ? iv[1] : (jj == 2) ? iv[2] : iv[3];
; #pragma unroll
;     for (int u = 0; u < 8; ++u) { const int si = __builtin_amdgcn_readlane(ivb, l0 + u); buf[u] = __builtin_amdgcn_raw_buffer_load_b128(rs, voff, si * 2048 + sbase, KV8_AUX); }
; }
; __device__ __forceinline__ void kv8_pv(const u32x4 (&buf)[8], f32x2v (&o2)[8], const LAS float* srow, int b) {
;     const LAS f32x4* p4 = (const LAS f32x4*)(srow + b * 8);
;     const f32x4 p0 = p4[0], p1 = p4[1];
;     const float p[8] = {p0.x, p0.y, p0.z, p0.w, p1.x, p1.y, p1.z, p1.w};
; #pragma unroll
;     for (int u = 0; u < 8; ++u) {
;         const u32x4 v = buf[u]; const f32x2v pp = {p[u], p[u]};
;         o2[0] = __builtin_elementwise_fma(pp, __builtin_amdgcn_cvt_pk_f32_fp8(v.x, false), o2[0]); o2[1] = __builtin_elementwise_fma(pp, __builtin_amdgcn_cvt_pk_f32_fp8(v.x, true), o2[1]);
;         o2[2] = __builtin_elementwise_fma(pp, __builtin_amdgcn_cvt_pk_f32_fp8(v.y, false), o2[2]); o2[3] = __builtin_elementwise_fma(pp, __builtin_amdgcn_cvt_pk_f32_fp8(v.y, true), o2[3]);
;         o2[4] = __builtin_elementwise_fma(pp, __builtin_amdgcn_cvt_pk_f32_fp8(v.z, false), o2[4]); o2[5] = __builtin_elementwise_fma(pp, __builtin_amdgcn_cvt_pk_f32_fp8(v.z, true), o2[5]);
;         o2[6] = __builtin_elementwise_fma(pp, __builtin_amdgcn_cvt_pk_f32_fp8(v.w, false), o2[6]); o2[7] = __builtin_elementwise_fma(pp, __builtin_amdgcn_cvt_pk_f32_fp8(v.w, true), o2[7]);
;     }
	v_cvt_pk_f32_fp8_e32 v[214:215], v24
	v_cvt_pk_f32_fp8_sdwa v[216:217], v24 src0_sel:WORD_1
	v_pk_fma_f32 v[198:199], v[156:157], v[214:215], v[198:199] op_sel_hi:[0,1,1]
	v_pk_fma_f32 v[200:201], v[156:157], v[216:217], v[200:201] op_sel_hi:[0,1,1]
	v_cvt_pk_f32_fp8_e32 v[218:219], v25
	v_cvt_pk_f32_fp8_sdwa v[220:221], v25 src0_sel:WORD_1
	v_pk_fma_f32 v[202:203], v[156:157], v[218:219], v[202:203] op_sel_hi:[0,1,1]
	v_pk_fma_f32 v[204:205], v[156:157], v[220:221], v[204:205] op_sel_hi:[0,1,1]
	v_cvt_pk_f32_fp8_e32 v[214:215], v26
	v_cvt_pk_f32_fp8_sdwa v[216:217], v26 src0_sel:WORD_1
	v_pk_fma_f32 v[206:207], v[156:157], v[214:215], v[206:207] op_sel_hi:[0,1,1]
	v_pk_fma_f32 v[208:209], v[156:157], v[216:217], v[208:209] op_sel_hi:[0,1,1]
	v_cvt_pk_f32_fp8_e32 v[218:219], v27
	v_cvt_pk_f32_fp8_sdwa v[220:221], v27 src0_sel:WORD_1
	v_pk_fma_f32 v[210:211], v[156:157], v[218:219], v[210:211] op_sel_hi:[0,1,1]
	v_pk_fma_f32 v[212:213], v[156:157], v[220:221], v[212:213] op_sel_hi:[0,1,1]
	s_waitcnt vmcnt(28)
	v_cvt_pk_f32_fp8_e32 v[214:215], v28
	v_cvt_pk_f32_fp8_sdwa v[216:217], v28 src0_sel:WORD_1
	v_pk_fma_f32 v[198:199], v[156:157], v[214:215], v[198:199] op_sel:[1,0,0]
	v_pk_fma_f32 v[200:201], v[156:157], v[216:217], v[200:201] op_sel:[1,0,0]
	v_cvt_pk_f32_fp8_e32 v[218:219], v29
	v_cvt_pk_f32_fp8_sdwa v[220:221], v29 src0_sel:WORD_1
	v_pk_fma_f32 v[202:203], v[156:157], v[218:219], v[202:203] op_sel:[1,0,0]
	v_pk_fma_f32 v[204:205], v[156:157], v[220:221], v[204:205] op_sel:[1,0,0]
	v_cvt_pk_f32_fp8_e32 v[214:215], v30
	v_cvt_pk_f32_fp8_sdwa v[216:217], v30 src0_sel:WORD_1
	v_pk_fma_f32 v[206:207], v[156:157], v[214:215], v[206:207] op_sel:[1,0,0]
	v_pk_fma_f32 v[208:209], v[156:157], v[216:217], v[208:209] op_sel:[1,0,0]
	v_cvt_pk_f32_fp8_e32 v[218:219], v31
	v_cvt_pk_f32_fp8_sdwa v[220:221], v31 src0_sel:WORD_1
	v_pk_fma_f32 v[210:211], v[156:157], v[218:219], v[210:211] op_sel:[1,0,0]
	v_pk_fma_f32 v[212:213], v[156:157], v[220:221], v[212:213] op_sel:[1,0,0]
	ds_read_b128 v[154:157], v139 offset:16
	s_waitcnt vmcnt(27)
	v_cvt_pk_f32_fp8_e32 v[214:215], v32
	v_cvt_pk_f32_fp8_sdwa v[216:217], v32 src0_sel:WORD_1
	v_pk_fma_f32 v[198:199], v[158:159], v[214:215], v[198:199] op_sel_hi:[0,1,1]
	v_pk_fma_f32 v[200:201], v[158:159], v[216:217], v[200:201] op_sel_hi:[0,1,1]
	v_cvt_pk_f32_fp8_e32 v[218:219], v33
	v_cvt_pk_f32_fp8_sdwa v[220:221], v33 src0_sel:WORD_1
	v_pk_fma_f32 v[202:203], v[158:159], v[218:219], v[202:203] op_sel_hi:[0,1,1]
	v_pk_fma_f32 v[204:205], v[158:159], v[220:221], v[204:205] op_sel_hi:[0,1,1]
	v_cvt_pk_f32_fp8_e32 v[214:215], v34
	v_cvt_pk_f32_fp8_sdwa v[216:217], v34 src0_sel:WORD_1
	v_pk_fma_f32 v[206:207], v[158:159], v[214:215], v[206:207] op_sel_hi:[0,1,1]
	v_pk_fma_f32 v[208:209], v[158:159], v[216:217], v[208:209] op_sel_hi:[0,1,1]
	v_cvt_pk_f32_fp8_e32 v[218:219], v35
	v_cvt_pk_f32_fp8_sdwa v[220:221], v35 src0_sel:WORD_1
	v_pk_fma_f32 v[210:211], v[158:159], v[218:219], v[210:211] op_sel_hi:[0,1,1]
	v_pk_fma_f32 v[212:213], v[158:159], v[220:221], v[212:213] op_sel_hi:[0,1,1]
	s_waitcnt vmcnt(26)
	v_cvt_pk_f32_fp8_e32 v[214:215], v36
	v_cvt_pk_f32_fp8_sdwa v[216:217], v36 src0_sel:WORD_1
	v_pk_fma_f32 v[198:199], v[158:159], v[214:215], v[198:199] op_sel:[1,0,0]
	v_pk_fma_f32 v[200:201], v[158:159], v[216:217], v[200:201] op_sel:[1,0,0]
	v_cvt_pk_f32_fp8_e32 v[218:219], v37
	v_cvt_pk_f32_fp8_sdwa v[220:221], v37 src0_sel:WORD_1
	v_pk_fma_f32 v[202:203], v[158:159], v[218:219], v[202:203] op_sel:[1,0,0]
	v_pk_fma_f32 v[204:205], v[158:159], v[220:221], v[204:205] op_sel:[1,0,0]
	v_cvt_pk_f32_fp8_e32 v[214:215], v38
	v_cvt_pk_f32_fp8_sdwa v[216:217], v38 src0_sel:WORD_1
	v_pk_fma_f32 v[206:207], v[158:159], v[214:215], v[206:207] op_sel:[1,0,0]
	v_pk_fma_f32 v[208:209], v[158:159], v[216:217], v[208:209] op_sel:[1,0,0]
	v_cvt_pk_f32_fp8_e32 v[218:219], v39
	v_cvt_pk_f32_fp8_sdwa v[220:221], v39 src0_sel:WORD_1
	v_pk_fma_f32 v[210:211], v[158:159], v[218:219], v[210:211] op_sel:[1,0,0]
	v_pk_fma_f32 v[212:213], v[158:159], v[220:221], v[212:213] op_sel:[1,0,0]
	s_waitcnt lgkmcnt(0)
	v_lshl_add_u32 v154, v154, 8, v138
	v_lshl_add_u32 v155, v155, 8, v138
	v_lshl_add_u32 v156, v156, 8, v138
	v_lshl_add_u32 v157, v157, 8, v138
	buffer_load_dwordx4 v[16:19], v154, s[16:19], s26 offen
	buffer_load_dwordx4 v[20:23], v155, s[16:19], s26 offen
	buffer_load_dwordx4 v[24:27], v156, s[16:19], s26 offen
	buffer_load_dwordx4 v[28:31], v157, s[16:19], s26 offen
	s_waitcnt vmcnt(29)
	v_cvt_pk_f32_fp8_e32 v[214:215], v40
	v_cvt_pk_f32_fp8_sdwa v[216:217], v40 src0_sel:WORD_1
	v_pk_fma_f32 v[198:199], v[160:161], v[214:215], v[198:199] op_sel_hi:[0,1,1]
	v_pk_fma_f32 v[200:201], v[160:161], v[216:217], v[200:201] op_sel_hi:[0,1,1]
	v_cvt_pk_f32_fp8_e32 v[218:219], v41
	v_cvt_pk_f32_fp8_sdwa v[220:221], v41 src0_sel:WORD_1
	v_pk_fma_f32 v[202:203], v[160:161], v[218:219], v[202:203] op_sel_hi:[0,1,1]
	v_pk_fma_f32 v[204:205], v[160:161], v[220:221], v[204:205] op_sel_hi:[0,1,1]
	v_cvt_pk_f32_fp8_e32 v[214:215], v42
	v_cvt_pk_f32_fp8_sdwa v[216:217], v42 src0_sel:WORD_1
	v_pk_fma_f32 v[206:207], v[160:161], v[214:215], v[206:207] op_sel_hi:[0,1,1]
	v_pk_fma_f32 v[208:209], v[160:161], v[216:217], v[208:209] op_sel_hi:[0,1,1]
	v_cvt_pk_f32_fp8_e32 v[218:219], v43
	v_cvt_pk_f32_fp8_sdwa v[220:221], v43 src0_sel:WORD_1
	v_pk_fma_f32 v[210:211], v[160:161], v[218:219], v[210:211] op_sel_hi:[0,1,1]
	v_pk_fma_f32 v[212:213], v[160:161], v[220:221], v[212:213] op_sel_hi:[0,1,1]
	s_waitcnt vmcnt(28)
; #define LAS __attribute__((address_space(3)))
; __device__ __forceinline__ void kv8_issue(u32x4 (&buf)[8], __amdgpu_buffer_rsrc_t rs, int voff  , int sbase  , const int (&iv)[4], int b) {
;     const int jj = b >> 3, l0 = (b & 7) * 8;
;     const int ivb = (jj == 0) ? iv[0] : (jj == 1) ? iv[1] : (jj == 2) ? iv[2] : iv[3];
; #pragma unroll
;     for (int u = 0; u < 8; ++u) { const int si = __builtin_amdgcn_readlane(ivb, l0 + u); buf[u] = __builtin_amdgcn_raw_buffer_load_b128(rs, voff, si * 2048 + sbase, KV8_AUX); }
; }
; __device__ __forceinline__ void kv8_pv(const u32x4 (&buf)[8], f32x2v (&o2)[8], const LAS float* srow, int b) {
;     const LAS f32x4* p4 = (const LAS f32x4*)(srow + b * 8);
;     const f32x4 p0 = p4[0], p1 = p4[1];
;     const float p[8] = {p0.x, p0.y, p0.z, p0.w, p1.x, p1.y, p1.z, p1.w};
; #pragma unroll
;     for (int u = 0; u < 8; ++u) {
;         const u32x4 v = buf[u]; const f32x2v pp = {p[u], p[u]};
;         o2[0] = __builtin_elementwise_fma(pp, __builtin_amdgcn_cvt_pk_f32_fp8(v.x, false), o2[0]); o2[1] = __builtin_elementwise_fma(pp, __builtin_amdgcn_cvt_pk_f32_fp8(v.x, true), o2[1]);
;         o2[2] = __builtin_elementwise_fma(pp, __builtin_amdgcn_cvt_pk_f32_fp8(v.y, false), o2[2]); o2[3] = __builtin_elementwise_fma(pp, __builtin_amdgcn_cvt_pk_f32_fp8(v.y, true), o2[3]);
;         o2[4] = __builtin_elementwise_fma(pp, __builtin_amdgcn_cvt_pk_f32_fp8(v.z, false), o2[4]); o2[5] = __builtin_elementwise_fma(pp, __builtin_amdgcn_cvt_pk_f32_fp8(v.z, true), o2[5]);
;         o2[6] = __builtin_elementwise_fma(pp, __builtin_amdgcn_cvt_pk_f32_fp8(v.w, false), o2[6]); o2[7] = __builtin_elementwise_fma(pp, __builtin_amdgcn_cvt_pk_f32_fp8(v.w, true), o2[7]);
;     }
	v_cvt_pk_f32_fp8_e32 v[214:215], v44
	v_cvt_pk_f32_fp8_sdwa v[216:217], v44 src0_sel:WORD_1
	v_pk_fma_f32 v[198:199], v[160:161], v[214:215], v[198:199] op_sel:[1,0,0]
	v_pk_fma_f32 v[200:201], v[160:161], v[216:217], v[200:201] op_sel:[1,0,0]
	v_cvt_pk_f32_fp8_e32 v[218:219], v45
	v_cvt_pk_f32_fp8_sdwa v[220:221], v45 src0_sel:WORD_1
	v_pk_fma_f32 v[202:203], v[160:161], v[218:219], v[202:203] op_sel:[1,0,0]
	v_pk_fma_f32 v[204:205], v[160:161], v[220:221], v[204:205] op_sel:[1,0,0]
	v_cvt_pk_f32_fp8_e32 v[214:215], v46
	v_cvt_pk_f32_fp8_sdwa v[216:217], v46 src0_sel:WORD_1
	v_pk_fma_f32 v[206:207], v[160:161], v[214:215], v[206:207] op_sel:[1,0,0]
	v_pk_fma_f32 v[208:209], v[160:161], v[216:217], v[208:209] op_sel:[1,0,0]
	v_cvt_pk_f32_fp8_e32 v[218:219], v47
	v_cvt_pk_f32_fp8_sdwa v[220:221], v47 src0_sel:WORD_1
	v_pk_fma_f32 v[210:211], v[160:161], v[218:219], v[210:211] op_sel:[1,0,0]
	v_pk_fma_f32 v[212:213], v[160:161], v[220:221], v[212:213] op_sel:[1,0,0]
	ds_read_b128 v[158:161], v139 offset:32
	s_waitcnt vmcnt(27)
	v_cvt_pk_f32_fp8_e32 v[214:215], v48
	v_cvt_pk_f32_fp8_sdwa v[216:217], v48 src0_sel:WORD_1
	v_pk_fma_f32 v[198:199], v[162:163], v[214:215], v[198:199] op_sel_hi:[0,1,1]
	v_pk_fma_f32 v[200:201], v[162:163], v[216:217], v[200:201] op_sel_hi:[0,1,1]
	v_cvt_pk_f32_fp8_e32 v[218:219], v49
	v_cvt_pk_f32_fp8_sdwa v[220:221], v49 src0_sel:WORD_1
	v_pk_fma_f32 v[202:203], v[162:163], v[218:219], v[202:203] op_sel_hi:[0,1,1]
	v_pk_fma_f32 v[204:205], v[162:163], v[220:221], v[204:205] op_sel_hi:[0,1,1]
	v_cvt_pk_f32_fp8_e32 v[214:215], v50
	v_cvt_pk_f32_fp8_sdwa v[216:217], v50 src0_sel:WORD_1
	v_pk_fma_f32 v[206:207], v[162:163], v[214:215], v[206:207] op_sel_hi:[0,1,1]
	v_pk_fma_f32 v[208:209], v[162:163], v[216:217], v[208:209] op_sel_hi:[0,1,1]
	v_cvt_pk_f32_fp8_e32 v[218:219], v51
	v_cvt_pk_f32_fp8_sdwa v[220:221], v51 src0_sel:WORD_1
	v_pk_fma_f32 v[210:211], v[162:163], v[218:219], v[210:211] op_sel_hi:[0,1,1]
	v_pk_fma_f32 v[212:213], v[162:163], v[220:221], v[212:213] op_sel_hi:[0,1,1]
	s_waitcnt vmcnt(26)
	v_cvt_pk_f32_fp8_e32 v[214:215], v52
	v_cvt_pk_f32_fp8_sdwa v[216:217], v52 src0_sel:WORD_1
	v_pk_fma_f32 v[198:199], v[162:163], v[214:215], v[198:199] op_sel:[1,0,0]
	v_pk_fma_f32 v[200:201], v[162:163], v[216:217], v[200:201] op_sel:[1,0,0]
	v_cvt_pk_f32_fp8_e32 v[218:219], v53
	v_cvt_pk_f32_fp8_sdwa v[220:221], v53 src0_sel:WORD_1
	v_pk_fma_f32 v[202:203], v[162:163], v[218:219], v[202:203] op_sel:[1,0,0]
	v_pk_fma_f32 v[204:205], v[162:163], v[220:221], v[204:205] op_sel:[1,0,0]
	v_cvt_pk_f32_fp8_e32 v[214:215], v54
	v_cvt_pk_f32_fp8_sdwa v[216:217], v54 src0_sel:WORD_1
	v_pk_fma_f32 v[206:207], v[162:163], v[214:215], v[206:207] op_sel:[1,0,0]
	v_pk_fma_f32 v[208:209], v[162:163], v[216:217], v[208:209] op_sel:[1,0,0]
	v_cvt_pk_f32_fp8_e32 v[218:219], v55
	v_cvt_pk_f32_fp8_sdwa v[220:221], v55 src0_sel:WORD_1
	v_pk_fma_f32 v[210:211], v[162:163], v[218:219], v[210:211] op_sel:[1,0,0]
	v_pk_fma_f32 v[212:213], v[162:163], v[220:221], v[212:213] op_sel:[1,0,0]
	s_waitcnt lgkmcnt(0)
	v_lshl_add_u32 v158, v158, 8, v138
	v_lshl_add_u32 v159, v159, 8, v138
	v_lshl_add_u32 v160, v160, 8, v138
	v_lshl_add_u32 v161, v161, 8, v138
	buffer_load_dwordx4 v[32:35], v158, s[16:19], s26 offen
	buffer_load_dwordx4 v[36:39], v159, s[16:19], s26 offen
	buffer_load_dwordx4 v[40:43], v160, s[16:19], s26 offen
	buffer_load_dwordx4 v[44:47], v161, s[16:19], s26 offen
	s_waitcnt vmcnt(29)
	v_cvt_pk_f32_fp8_e32 v[214:215], v56
	v_cvt_pk_f32_fp8_sdwa v[216:217], v56 src0_sel:WORD_1
	v_pk_fma_f32 v[198:199], v[164:165], v[214:215], v[198:199] op_sel_hi:[0,1,1]
	v_pk_fma_f32 v[200:201], v[164:165], v[216:217], v[200:201] op_sel_hi:[0,1,1]
	v_cvt_pk_f32_fp8_e32 v[218:219], v57
	v_cvt_pk_f32_fp8_sdwa v[220:221], v57 src0_sel:WORD_1
	v_pk_fma_f32 v[202:203], v[164:165], v[218:219], v[202:203] op_sel_hi:[0,1,1]
	v_pk_fma_f32 v[204:205], v[164:165], v[220:221], v[204:205] op_sel_hi:[0,1,1]
	v_cvt_pk_f32_fp8_e32 v[214:215], v58
	v_cvt_pk_f32_fp8_sdwa v[216:217], v58 src0_sel:WORD_1
	v_pk_fma_f32 v[206:207], v[164:165], v[214:215], v[206:207] op_sel_hi:[0,1,1]
	v_pk_fma_f32 v[208:209], v[164:165], v[216:217], v[208:209] op_sel_hi:[0,1,1]
	v_cvt_pk_f32_fp8_e32 v[218:219], v59
	v_cvt_pk_f32_fp8_sdwa v[220:221], v59 src0_sel:WORD_1
	v_pk_fma_f32 v[210:211], v[164:165], v[218:219], v[210:211] op_sel_hi:[0,1,1]
	v_pk_fma_f32 v[212:213], v[164:165], v[220:221], v[212:213] op_sel_hi:[0,1,1]
	s_waitcnt vmcnt(28)
	v_cvt_pk_f32_fp8_e32 v[214:215], v60
	v_cvt_pk_f32_fp8_sdwa v[216:217], v60 src0_sel:WORD_1
	v_pk_fma_f32 v[198:199], v[164:165], v[214:215], v[198:199] op_sel:[1,0,0]
	v_pk_fma_f32 v[200:201], v[164:165], v[216:217], v[200:201] op_sel:[1,0,0]
	v_cvt_pk_f32_fp8_e32 v[218:219], v61
	v_cvt_pk_f32_fp8_sdwa v[220:221], v61 src0_sel:WORD_1
	v_pk_fma_f32 v[202:203], v[164:165], v[218:219], v[202:203] op_sel:[1,0,0]
	v_pk_fma_f32 v[204:205], v[164:165], v[220:221], v[204:205] op_sel:[1,0,0]
	v_cvt_pk_f32_fp8_e32 v[214:215], v62
	v_cvt_pk_f32_fp8_sdwa v[216:217], v62 src0_sel:WORD_1
	v_pk_fma_f32 v[206:207], v[164:165], v[214:215], v[206:207] op_sel:[1,0,0]
	v_pk_fma_f32 v[208:209], v[164:165], v[216:217], v[208:209] op_sel:[1,0,0]
	v_cvt_pk_f32_fp8_e32 v[218:219], v63
	v_cvt_pk_f32_fp8_sdwa v[220:221], v63 src0_sel:WORD_1
	v_pk_fma_f32 v[210:211], v[164:165], v[218:219], v[210:211] op_sel:[1,0,0]
	v_pk_fma_f32 v[212:213], v[164:165], v[220:221], v[212:213] op_sel:[1,0,0]
	ds_read_b128 v[162:165], v139 offset:48
	s_waitcnt vmcnt(27)
; #define LAS __attribute__((address_space(3)))
; __device__ __forceinline__ void kv8_issue(u32x4 (&buf)[8], __amdgpu_buffer_rsrc_t rs, int voff  , int sbase  , const int (&iv)[4], int b) {
;     const int jj = b >> 3, l0 = (b & 7) * 8;
;     const int ivb = (jj == 0) ? iv[0] : (jj == 1) ? iv[1] : (jj == 2) ? iv[2] : iv[3];
; #pragma unroll
;     for (int u = 0; u < 8; ++u) { const int si = __builtin_amdgcn_readlane(ivb, l0 + u); buf[u] = __builtin_amdgcn_raw_buffer_load_b128(rs, voff, si * 2048 + sbase, KV8_AUX); }
; }
; __device__ __forceinline__ void kv8_pv(const u32x4 (&buf)[8], f32x2v (&o2)[8], const LAS float* srow, int b) {
;     const LAS f32x4* p4 = (const LAS f32x4*)(srow + b * 8);
;     const f32x4 p0 = p4[0], p1 = p4[1];
;     const float p[8] = {p0.x, p0.y, p0.z, p0.w, p1.x, p1.y, p1.z, p1.w};
; #pragma unroll
;     for (int u = 0; u < 8; ++u) {
;         const u32x4 v = buf[u]; const f32x2v pp = {p[u], p[u]};
;         o2[0] = __builtin_elementwise_fma(pp, __builtin_amdgcn_cvt_pk_f32_fp8(v.x, false), o2[0]); o2[1] = __builtin_elementwise_fma(pp, __builtin_amdgcn_cvt_pk_f32_fp8(v.x, true), o2[1]);
;         o2[2] = __builtin_elementwise_fma(pp, __builtin_amdgcn_cvt_pk_f32_fp8(v.y, false), o2[2]); o2[3] = __builtin_elementwise_fma(pp, __builtin_amdgcn_cvt_pk_f32_fp8(v.y, true), o2[3]);
;         o2[4] = __builtin_elementwise_fma(pp, __builtin_amdgcn_cvt_pk_f32_fp8(v.z, false), o2[4]); o2[5] = __builtin_elementwise_fma(pp, __builtin_amdgcn_cvt_pk_f32_fp8(v.z, true), o2[5]);
;         o2[6] = __builtin_elementwise_fma(pp, __builtin_amdgcn_cvt_pk_f32_fp8(v.w, false), o2[6]); o2[7] = __builtin_elementwise_fma(pp, __builtin_amdgcn_cvt_pk_f32_fp8(v.w, true), o2[7]);
;     }
	v_cvt_pk_f32_fp8_e32 v[214:215], v64
	v_cvt_pk_f32_fp8_sdwa v[216:217], v64 src0_sel:WORD_1
	v_pk_fma_f32 v[198:199], v[166:167], v[214:215], v[198:199] op_sel_hi:[0,1,1]
	v_pk_fma_f32 v[200:201], v[166:167], v[216:217], v[200:201] op_sel_hi:[0,1,1]
	v_cvt_pk_f32_fp8_e32 v[218:219], v65
	v_cvt_pk_f32_fp8_sdwa v[220:221], v65 src0_sel:WORD_1
	v_pk_fma_f32 v[202:203], v[166:167], v[218:219], v[202:203] op_sel_hi:[0,1,1]
	v_pk_fma_f32 v[204:205], v[166:167], v[220:221], v[204:205] op_sel_hi:[0,1,1]
	v_cvt_pk_f32_fp8_e32 v[214:215], v66
	v_cvt_pk_f32_fp8_sdwa v[216:217], v66 src0_sel:WORD_1
	v_pk_fma_f32 v[206:207], v[166:167], v[214:215], v[206:207] op_sel_hi:[0,1,1]
	v_pk_fma_f32 v[208:209], v[166:167], v[216:217], v[208:209] op_sel_hi:[0,1,1]
	v_cvt_pk_f32_fp8_e32 v[218:219], v67
	v_cvt_pk_f32_fp8_sdwa v[220:221], v67 src0_sel:WORD_1
	v_pk_fma_f32 v[210:211], v[166:167], v[218:219], v[210:211] op_sel_hi:[0,1,1]
	v_pk_fma_f32 v[212:213], v[166:167], v[220:221], v[212:213] op_sel_hi:[0,1,1]
	s_waitcnt vmcnt(26)
	v_cvt_pk_f32_fp8_e32 v[214:215], v68
	v_cvt_pk_f32_fp8_sdwa v[216:217], v68 src0_sel:WORD_1
	v_pk_fma_f32 v[198:199], v[166:167], v[214:215], v[198:199] op_sel:[1,0,0]
	v_pk_fma_f32 v[200:201], v[166:167], v[216:217], v[200:201] op_sel:[1,0,0]
	v_cvt_pk_f32_fp8_e32 v[218:219], v69
	v_cvt_pk_f32_fp8_sdwa v[220:221], v69 src0_sel:WORD_1
	v_pk_fma_f32 v[202:203], v[166:167], v[218:219], v[202:203] op_sel:[1,0,0]
	v_pk_fma_f32 v[204:205], v[166:167], v[220:221], v[204:205] op_sel:[1,0,0]
	v_cvt_pk_f32_fp8_e32 v[214:215], v70
	v_cvt_pk_f32_fp8_sdwa v[216:217], v70 src0_sel:WORD_1
	v_pk_fma_f32 v[206:207], v[166:167], v[214:215], v[206:207] op_sel:[1,0,0]
	v_pk_fma_f32 v[208:209], v[166:167], v[216:217], v[208:209] op_sel:[1,0,0]
	v_cvt_pk_f32_fp8_e32 v[218:219], v71
	v_cvt_pk_f32_fp8_sdwa v[220:221], v71 src0_sel:WORD_1
	v_pk_fma_f32 v[210:211], v[166:167], v[218:219], v[210:211] op_sel:[1,0,0]
	v_pk_fma_f32 v[212:213], v[166:167], v[220:221], v[212:213] op_sel:[1,0,0]
	s_waitcnt lgkmcnt(0)
	v_lshl_add_u32 v162, v162, 8, v138
	v_lshl_add_u32 v163, v163, 8, v138
	v_lshl_add_u32 v164, v164, 8, v138
	v_lshl_add_u32 v165, v165, 8, v138
	buffer_load_dwordx4 v[48:51], v162, s[16:19], s26 offen
	buffer_load_dwordx4 v[52:55], v163, s[16:19], s26 offen
	buffer_load_dwordx4 v[56:59], v164, s[16:19], s26 offen
	buffer_load_dwordx4 v[60:63], v165, s[16:19], s26 offen
	s_waitcnt vmcnt(29)
	v_cvt_pk_f32_fp8_e32 v[214:215], v72
	v_cvt_pk_f32_fp8_sdwa v[216:217], v72 src0_sel:WORD_1
	v_pk_fma_f32 v[198:199], v[168:169], v[214:215], v[198:199] op_sel_hi:[0,1,1]
	v_pk_fma_f32 v[200:201], v[168:169], v[216:217], v[200:201] op_sel_hi:[0,1,1]
	v_cvt_pk_f32_fp8_e32 v[218:219], v73
	v_cvt_pk_f32_fp8_sdwa v[220:221], v73 src0_sel:WORD_1
	v_pk_fma_f32 v[202:203], v[168:169], v[218:219], v[202:203] op_sel_hi:[0,1,1]
	v_pk_fma_f32 v[204:205], v[168:169], v[220:221], v[204:205] op_sel_hi:[0,1,1]
	v_cvt_pk_f32_fp8_e32 v[214:215], v74
	v_cvt_pk_f32_fp8_sdwa v[216:217], v74 src0_sel:WORD_1
	v_pk_fma_f32 v[206:207], v[168:169], v[214:215], v[206:207] op_sel_hi:[0,1,1]
	v_pk_fma_f32 v[208:209], v[168:169], v[216:217], v[208:209] op_sel_hi:[0,1,1]
	v_cvt_pk_f32_fp8_e32 v[218:219], v75
	v_cvt_pk_f32_fp8_sdwa v[220:221], v75 src0_sel:WORD_1
	v_pk_fma_f32 v[210:211], v[168:169], v[218:219], v[210:211] op_sel_hi:[0,1,1]
	v_pk_fma_f32 v[212:213], v[168:169], v[220:221], v[212:213] op_sel_hi:[0,1,1]
	s_waitcnt vmcnt(28)
	v_cvt_pk_f32_fp8_e32 v[214:215], v76
	v_cvt_pk_f32_fp8_sdwa v[216:217], v76 src0_sel:WORD_1
	v_pk_fma_f32 v[198:199], v[168:169], v[214:215], v[198:199] op_sel:[1,0,0]
	v_pk_fma_f32 v[200:201], v[168:169], v[216:217], v[200:201] op_sel:[1,0,0]
	v_cvt_pk_f32_fp8_e32 v[218:219], v77
	v_cvt_pk_f32_fp8_sdwa v[220:221], v77 src0_sel:WORD_1
	v_pk_fma_f32 v[202:203], v[168:169], v[218:219], v[202:203] op_sel:[1,0,0]
	v_pk_fma_f32 v[204:205], v[168:169], v[220:221], v[204:205] op_sel:[1,0,0]
	v_cvt_pk_f32_fp8_e32 v[214:215], v78
	v_cvt_pk_f32_fp8_sdwa v[216:217], v78 src0_sel:WORD_1
	v_pk_fma_f32 v[206:207], v[168:169], v[214:215], v[206:207] op_sel:[1,0,0]
	v_pk_fma_f32 v[208:209], v[168:169], v[216:217], v[208:209] op_sel:[1,0,0]
	v_cvt_pk_f32_fp8_e32 v[218:219], v79
	v_cvt_pk_f32_fp8_sdwa v[220:221], v79 src0_sel:WORD_1
	v_pk_fma_f32 v[210:211], v[168:169], v[218:219], v[210:211] op_sel:[1,0,0]
	v_pk_fma_f32 v[212:213], v[168:169], v[220:221], v[212:213] op_sel:[1,0,0]
	ds_read_b128 v[166:169], v139 offset:64
	s_waitcnt vmcnt(27)
	v_cvt_pk_f32_fp8_e32 v[214:215], v80
	v_cvt_pk_f32_fp8_sdwa v[216:217], v80 src0_sel:WORD_1
	v_pk_fma_f32 v[198:199], v[170:171], v[214:215], v[198:199] op_sel_hi:[0,1,1]
	v_pk_fma_f32 v[200:201], v[170:171], v[216:217], v[200:201] op_sel_hi:[0,1,1]
	v_cvt_pk_f32_fp8_e32 v[218:219], v81
	v_cvt_pk_f32_fp8_sdwa v[220:221], v81 src0_sel:WORD_1
	v_pk_fma_f32 v[202:203], v[170:171], v[218:219], v[202:203] op_sel_hi:[0,1,1]
	v_pk_fma_f32 v[204:205], v[170:171], v[220:221], v[204:205] op_sel_hi:[0,1,1]
	v_cvt_pk_f32_fp8_e32 v[214:215], v82
	v_cvt_pk_f32_fp8_sdwa v[216:217], v82 src0_sel:WORD_1
	v_pk_fma_f32 v[206:207], v[170:171], v[214:215], v[206:207] op_sel_hi:[0,1,1]
	v_pk_fma_f32 v[208:209], v[170:171], v[216:217], v[208:209] op_sel_hi:[0,1,1]
	v_cvt_pk_f32_fp8_e32 v[218:219], v83
	v_cvt_pk_f32_fp8_sdwa v[220:221], v83 src0_sel:WORD_1
	v_pk_fma_f32 v[210:211], v[170:171], v[218:219], v[210:211] op_sel_hi:[0,1,1]
	v_pk_fma_f32 v[212:213], v[170:171], v[220:221], v[212:213] op_sel_hi:[0,1,1]
	s_waitcnt vmcnt(26)
; #define LAS __attribute__((address_space(3)))
; __device__ __forceinline__ void kv8_issue(u32x4 (&buf)[8], __amdgpu_buffer_rsrc_t rs, int voff  , int sbase  , const int (&iv)[4], int b) {
;     const int jj = b >> 3, l0 = (b & 7) * 8;
;     const int ivb = (jj == 0) ? iv[0] : (jj == 1) ? iv[1] : (jj == 2) ? iv[2] : iv[3];
; #pragma unroll
;     for (int u = 0; u < 8; ++u) { const int si = __builtin_amdgcn_readlane(ivb, l0 + u); buf[u] = __builtin_amdgcn_raw_buffer_load_b128(rs, voff, si * 2048 + sbase, KV8_AUX); }
; }
; __device__ __forceinline__ void kv8_pv(const u32x4 (&buf)[8], f32x2v (&o2)[8], const LAS float* srow, int b) {
;     const LAS f32x4* p4 = (const LAS f32x4*)(srow + b * 8);
;     const f32x4 p0 = p4[0], p1 = p4[1];
;     const float p[8] = {p0.x, p0.y, p0.z, p0.w, p1.x, p1.y, p1.z, p1.w};
; #pragma unroll
;     for (int u = 0; u < 8; ++u) {
;         const u32x4 v = buf[u]; const f32x2v pp = {p[u], p[u]};
;         o2[0] = __builtin_elementwise_fma(pp, __builtin_amdgcn_cvt_pk_f32_fp8(v.x, false), o2[0]); o2[1] = __builtin_elementwise_fma(pp, __builtin_amdgcn_cvt_pk_f32_fp8(v.x, true), o2[1]);
;         o2[2] = __builtin_elementwise_fma(pp, __builtin_amdgcn_cvt_pk_f32_fp8(v.y, false), o2[2]); o2[3] = __builtin_elementwise_fma(pp, __builtin_amdgcn_cvt_pk_f32_fp8(v.y, true), o2[3]);
;         o2[4] = __builtin_elementwise_fma(pp, __builtin_amdgcn_cvt_pk_f32_fp8(v.z, false), o2[4]); o2[5] = __builtin_elementwise_fma(pp, __builtin_amdgcn_cvt_pk_f32_fp8(v.z, true), o2[5]);
;         o2[6] = __builtin_elementwise_fma(pp, __builtin_amdgcn_cvt_pk_f32_fp8(v.w, false), o2[6]); o2[7] = __builtin_elementwise_fma(pp, __builtin_amdgcn_cvt_pk_f32_fp8(v.w, true), o2[7]);
;     }
	v_cvt_pk_f32_fp8_e32 v[214:215], v84
	v_cvt_pk_f32_fp8_sdwa v[216:217], v84 src0_sel:WORD_1
	v_pk_fma_f32 v[198:199], v[170:171], v[214:215], v[198:199] op_sel:[1,0,0]
	v_pk_fma_f32 v[200:201], v[170:171], v[216:217], v[200:201] op_sel:[1,0,0]
	v_cvt_pk_f32_fp8_e32 v[218:219], v85
	v_cvt_pk_f32_fp8_sdwa v[220:221], v85 src0_sel:WORD_1
	v_pk_fma_f32 v[202:203], v[170:171], v[218:219], v[202:203] op_sel:[1,0,0]
	v_pk_fma_f32 v[204:205], v[170:171], v[220:221], v[204:205] op_sel:[1,0,0]
	v_cvt_pk_f32_fp8_e32 v[214:215], v86
	v_cvt_pk_f32_fp8_sdwa v[216:217], v86 src0_sel:WORD_1
	v_pk_fma_f32 v[206:207], v[170:171], v[214:215], v[206:207] op_sel:[1,0,0]
	v_pk_fma_f32 v[208:209], v[170:171], v[216:217], v[208:209] op_sel:[1,0,0]
	v_cvt_pk_f32_fp8_e32 v[218:219], v87
	v_cvt_pk_f32_fp8_sdwa v[220:221], v87 src0_sel:WORD_1
	v_pk_fma_f32 v[210:211], v[170:171], v[218:219], v[210:211] op_sel:[1,0,0]
	v_pk_fma_f32 v[212:213], v[170:171], v[220:221], v[212:213] op_sel:[1,0,0]
	s_waitcnt lgkmcnt(0)
	v_lshl_add_u32 v166, v166, 8, v138
	v_lshl_add_u32 v167, v167, 8, v138
	v_lshl_add_u32 v168, v168, 8, v138
	v_lshl_add_u32 v169, v169, 8, v138
	buffer_load_dwordx4 v[64:67], v166, s[16:19], s26 offen
	buffer_load_dwordx4 v[68:71], v167, s[16:19], s26 offen
	buffer_load_dwordx4 v[72:75], v168, s[16:19], s26 offen
	buffer_load_dwordx4 v[76:79], v169, s[16:19], s26 offen
	s_waitcnt vmcnt(29)
	v_cvt_pk_f32_fp8_e32 v[214:215], v88
	v_cvt_pk_f32_fp8_sdwa v[216:217], v88 src0_sel:WORD_1
	v_pk_fma_f32 v[198:199], v[172:173], v[214:215], v[198:199] op_sel_hi:[0,1,1]
	v_pk_fma_f32 v[200:201], v[172:173], v[216:217], v[200:201] op_sel_hi:[0,1,1]
	v_cvt_pk_f32_fp8_e32 v[218:219], v89
	v_cvt_pk_f32_fp8_sdwa v[220:221], v89 src0_sel:WORD_1
	v_pk_fma_f32 v[202:203], v[172:173], v[218:219], v[202:203] op_sel_hi:[0,1,1]
	v_pk_fma_f32 v[204:205], v[172:173], v[220:221], v[204:205] op_sel_hi:[0,1,1]
	v_cvt_pk_f32_fp8_e32 v[214:215], v90
	v_cvt_pk_f32_fp8_sdwa v[216:217], v90 src0_sel:WORD_1
	v_pk_fma_f32 v[206:207], v[172:173], v[214:215], v[206:207] op_sel_hi:[0,1,1]
	v_pk_fma_f32 v[208:209], v[172:173], v[216:217], v[208:209] op_sel_hi:[0,1,1]
	v_cvt_pk_f32_fp8_e32 v[218:219], v91
	v_cvt_pk_f32_fp8_sdwa v[220:221], v91 src0_sel:WORD_1
	v_pk_fma_f32 v[210:211], v[172:173], v[218:219], v[210:211] op_sel_hi:[0,1,1]
	v_pk_fma_f32 v[212:213], v[172:173], v[220:221], v[212:213] op_sel_hi:[0,1,1]
	s_waitcnt vmcnt(28)
	v_cvt_pk_f32_fp8_e32 v[214:215], v92
	v_cvt_pk_f32_fp8_sdwa v[216:217], v92 src0_sel:WORD_1
	v_pk_fma_f32 v[198:199], v[172:173], v[214:215], v[198:199] op_sel:[1,0,0]
	v_pk_fma_f32 v[200:201], v[172:173], v[216:217], v[200:201] op_sel:[1,0,0]
	v_cvt_pk_f32_fp8_e32 v[218:219], v93
	v_cvt_pk_f32_fp8_sdwa v[220:221], v93 src0_sel:WORD_1
	v_pk_fma_f32 v[202:203], v[172:173], v[218:219], v[202:203] op_sel:[1,0,0]
	v_pk_fma_f32 v[204:205], v[172:173], v[220:221], v[204:205] op_sel:[1,0,0]
	v_cvt_pk_f32_fp8_e32 v[214:215], v94
	v_cvt_pk_f32_fp8_sdwa v[216:217], v94 src0_sel:WORD_1
	v_pk_fma_f32 v[206:207], v[172:173], v[214:215], v[206:207] op_sel:[1,0,0]
	v_pk_fma_f32 v[208:209], v[172:173], v[216:217], v[208:209] op_sel:[1,0,0]
	v_cvt_pk_f32_fp8_e32 v[218:219], v95
	v_cvt_pk_f32_fp8_sdwa v[220:221], v95 src0_sel:WORD_1
	v_pk_fma_f32 v[210:211], v[172:173], v[218:219], v[210:211] op_sel:[1,0,0]
	v_pk_fma_f32 v[212:213], v[172:173], v[220:221], v[212:213] op_sel:[1,0,0]
	ds_read_b128 v[170:173], v139 offset:80
	s_waitcnt vmcnt(27)
	v_cvt_pk_f32_fp8_e32 v[214:215], v96
	v_cvt_pk_f32_fp8_sdwa v[216:217], v96 src0_sel:WORD_1
	v_pk_fma_f32 v[198:199], v[174:175], v[214:215], v[198:199] op_sel_hi:[0,1,1]
	v_pk_fma_f32 v[200:201], v[174:175], v[216:217], v[200:201] op_sel_hi:[0,1,1]
	v_cvt_pk_f32_fp8_e32 v[218:219], v97
	v_cvt_pk_f32_fp8_sdwa v[220:221], v97 src0_sel:WORD_1
	v_pk_fma_f32 v[202:203], v[174:175], v[218:219], v[202:203] op_sel_hi:[0,1,1]
	v_pk_fma_f32 v[204:205], v[174:175], v[220:221], v[204:205] op_sel_hi:[0,1,1]
	v_cvt_pk_f32_fp8_e32 v[214:215], v98
	v_cvt_pk_f32_fp8_sdwa v[216:217], v98 src0_sel:WORD_1
	v_pk_fma_f32 v[206:207], v[174:175], v[214:215], v[206:207] op_sel_hi:[0,1,1]
	v_pk_fma_f32 v[208:209], v[174:175], v[216:217], v[208:209] op_sel_hi:[0,1,1]
	v_cvt_pk_f32_fp8_e32 v[218:219], v99
	v_cvt_pk_f32_fp8_sdwa v[220:221], v99 src0_sel:WORD_1
	v_pk_fma_f32 v[210:211], v[174:175], v[218:219], v[210:211] op_sel_hi:[0,1,1]
	v_pk_fma_f32 v[212:213], v[174:175], v[220:221], v[212:213] op_sel_hi:[0,1,1]
	s_waitcnt vmcnt(26)
	v_cvt_pk_f32_fp8_e32 v[214:215], v100
	v_cvt_pk_f32_fp8_sdwa v[216:217], v100 src0_sel:WORD_1
	v_pk_fma_f32 v[198:199], v[174:175], v[214:215], v[198:199] op_sel:[1,0,0]
	v_pk_fma_f32 v[200:201], v[174:175], v[216:217], v[200:201] op_sel:[1,0,0]
	v_cvt_pk_f32_fp8_e32 v[218:219], v101
	v_cvt_pk_f32_fp8_sdwa v[220:221], v101 src0_sel:WORD_1
	v_pk_fma_f32 v[202:203], v[174:175], v[218:219], v[202:203] op_sel:[1,0,0]
	v_pk_fma_f32 v[204:205], v[174:175], v[220:221], v[204:205] op_sel:[1,0,0]
	v_cvt_pk_f32_fp8_e32 v[214:215], v102
	v_cvt_pk_f32_fp8_sdwa v[216:217], v102 src0_sel:WORD_1
	v_pk_fma_f32 v[206:207], v[174:175], v[214:215], v[206:207] op_sel:[1,0,0]
	v_pk_fma_f32 v[208:209], v[174:175], v[216:217], v[208:209] op_sel:[1,0,0]
	v_cvt_pk_f32_fp8_e32 v[218:219], v103
	v_cvt_pk_f32_fp8_sdwa v[220:221], v103 src0_sel:WORD_1
	v_pk_fma_f32 v[210:211], v[174:175], v[218:219], v[210:211] op_sel:[1,0,0]
	v_pk_fma_f32 v[212:213], v[174:175], v[220:221], v[212:213] op_sel:[1,0,0]
	s_waitcnt lgkmcnt(0)
; #define LAS __attribute__((address_space(3)))
; __device__ __forceinline__ void kv8_issue(u32x4 (&buf)[8], __amdgpu_buffer_rsrc_t rs, int voff  , int sbase  , const int (&iv)[4], int b) {
;     const int jj = b >> 3, l0 = (b & 7) * 8;
;     const int ivb = (jj == 0) ? iv[0] : (jj == 1) ? iv[1] : (jj == 2) ? iv[2] : iv[3];
; #pragma unroll
;     for (int u = 0; u < 8; ++u) { const int si = __builtin_amdgcn_readlane(ivb, l0 + u); buf[u] = __builtin_amdgcn_raw_buffer_load_b128(rs, voff, si * 2048 + sbase, KV8_AUX); }
; }
; __device__ __forceinline__ void kv8_pv(const u32x4 (&buf)[8], f32x2v (&o2)[8], const LAS float* srow, int b) {
;     const LAS f32x4* p4 = (const LAS f32x4*)(srow + b * 8);
;     const f32x4 p0 = p4[0], p1 = p4[1];
;     const float p[8] = {p0.x, p0.y, p0.z, p0.w, p1.x, p1.y, p1.z, p1.w};
; #pragma unroll
;     for (int u = 0; u < 8; ++u) {
;         const u32x4 v = buf[u]; const f32x2v pp = {p[u], p[u]};
;         o2[0] = __builtin_elementwise_fma(pp, __builtin_amdgcn_cvt_pk_f32_fp8(v.x, false), o2[0]); o2[1] = __builtin_elementwise_fma(pp, __builtin_amdgcn_cvt_pk_f32_fp8(v.x, true), o2[1]);
;         o2[2] = __builtin_elementwise_fma(pp, __builtin_amdgcn_cvt_pk_f32_fp8(v.y, false), o2[2]); o2[3] = __builtin_elementwise_fma(pp, __builtin_amdgcn_cvt_pk_f32_fp8(v.y, true), o2[3]);
;         o2[4] = __builtin_elementwise_fma(pp, __builtin_amdgcn_cvt_pk_f32_fp8(v.z, false), o2[4]); o2[5] = __builtin_elementwise_fma(pp, __builtin_amdgcn_cvt_pk_f32_fp8(v.z, true), o2[5]);
;         o2[6] = __builtin_elementwise_fma(pp, __builtin_amdgcn_cvt_pk_f32_fp8(v.w, false), o2[6]); o2[7] = __builtin_elementwise_fma(pp, __builtin_amdgcn_cvt_pk_f32_fp8(v.w, true), o2[7]);
;     }
	v_lshl_add_u32 v170, v170, 8, v138
	v_lshl_add_u32 v171, v171, 8, v138
	v_lshl_add_u32 v172, v172, 8, v138
	v_lshl_add_u32 v173, v173, 8, v138
	buffer_load_dwordx4 v[80:83], v170, s[16:19], s26 offen
	buffer_load_dwordx4 v[84:87], v171, s[16:19], s26 offen
	buffer_load_dwordx4 v[88:91], v172, s[16:19], s26 offen
	buffer_load_dwordx4 v[92:95], v173, s[16:19], s26 offen
	s_waitcnt vmcnt(29)
	v_cvt_pk_f32_fp8_e32 v[214:215], v104
	v_cvt_pk_f32_fp8_sdwa v[216:217], v104 src0_sel:WORD_1
	v_pk_fma_f32 v[198:199], v[176:177], v[214:215], v[198:199] op_sel_hi:[0,1,1]
	v_pk_fma_f32 v[200:201], v[176:177], v[216:217], v[200:201] op_sel_hi:[0,1,1]
	v_cvt_pk_f32_fp8_e32 v[218:219], v105
	v_cvt_pk_f32_fp8_sdwa v[220:221], v105 src0_sel:WORD_1
	v_pk_fma_f32 v[202:203], v[176:177], v[218:219], v[202:203] op_sel_hi:[0,1,1]
	v_pk_fma_f32 v[204:205], v[176:177], v[220:221], v[204:205] op_sel_hi:[0,1,1]
	v_cvt_pk_f32_fp8_e32 v[214:215], v106
	v_cvt_pk_f32_fp8_sdwa v[216:217], v106 src0_sel:WORD_1
	v_pk_fma_f32 v[206:207], v[176:177], v[214:215], v[206:207] op_sel_hi:[0,1,1]
	v_pk_fma_f32 v[208:209], v[176:177], v[216:217], v[208:209] op_sel_hi:[0,1,1]
	v_cvt_pk_f32_fp8_e32 v[218:219], v107
	v_cvt_pk_f32_fp8_sdwa v[220:221], v107 src0_sel:WORD_1
	v_pk_fma_f32 v[210:211], v[176:177], v[218:219], v[210:211] op_sel_hi:[0,1,1]
	v_pk_fma_f32 v[212:213], v[176:177], v[220:221], v[212:213] op_sel_hi:[0,1,1]
	s_waitcnt vmcnt(28)
	v_cvt_pk_f32_fp8_e32 v[214:215], v108
	v_cvt_pk_f32_fp8_sdwa v[216:217], v108 src0_sel:WORD_1
	v_pk_fma_f32 v[198:199], v[176:177], v[214:215], v[198:199] op_sel:[1,0,0]
	v_pk_fma_f32 v[200:201], v[176:177], v[216:217], v[200:201] op_sel:[1,0,0]
	v_cvt_pk_f32_fp8_e32 v[218:219], v109
	v_cvt_pk_f32_fp8_sdwa v[220:221], v109 src0_sel:WORD_1
	v_pk_fma_f32 v[202:203], v[176:177], v[218:219], v[202:203] op_sel:[1,0,0]
	v_pk_fma_f32 v[204:205], v[176:177], v[220:221], v[204:205] op_sel:[1,0,0]
	v_cvt_pk_f32_fp8_e32 v[214:215], v110
	v_cvt_pk_f32_fp8_sdwa v[216:217], v110 src0_sel:WORD_1
	v_pk_fma_f32 v[206:207], v[176:177], v[214:215], v[206:207] op_sel:[1,0,0]
	v_pk_fma_f32 v[208:209], v[176:177], v[216:217], v[208:209] op_sel:[1,0,0]
	v_cvt_pk_f32_fp8_e32 v[218:219], v111
	v_cvt_pk_f32_fp8_sdwa v[220:221], v111 src0_sel:WORD_1
	v_pk_fma_f32 v[210:211], v[176:177], v[218:219], v[210:211] op_sel:[1,0,0]
	v_pk_fma_f32 v[212:213], v[176:177], v[220:221], v[212:213] op_sel:[1,0,0]
	ds_read_b128 v[174:177], v139 offset:96
	s_waitcnt vmcnt(27)
	v_cvt_pk_f32_fp8_e32 v[214:215], v112
	v_cvt_pk_f32_fp8_sdwa v[216:217], v112 src0_sel:WORD_1
	v_pk_fma_f32 v[198:199], v[178:179], v[214:215], v[198:199] op_sel_hi:[0,1,1]
	v_pk_fma_f32 v[200:201], v[178:179], v[216:217], v[200:201] op_sel_hi:[0,1,1]
	v_cvt_pk_f32_fp8_e32 v[218:219], v113
	v_cvt_pk_f32_fp8_sdwa v[220:221], v113 src0_sel:WORD_1
	v_pk_fma_f32 v[202:203], v[178:179], v[218:219], v[202:203] op_sel_hi:[0,1,1]
	v_pk_fma_f32 v[204:205], v[178:179], v[220:221], v[204:205] op_sel_hi:[0,1,1]
	v_cvt_pk_f32_fp8_e32 v[214:215], v114
	v_cvt_pk_f32_fp8_sdwa v[216:217], v114 src0_sel:WORD_1
	v_pk_fma_f32 v[206:207], v[178:179], v[214:215], v[206:207] op_sel_hi:[0,1,1]
	v_pk_fma_f32 v[208:209], v[178:179], v[216:217], v[208:209] op_sel_hi:[0,1,1]
	v_cvt_pk_f32_fp8_e32 v[218:219], v115
	v_cvt_pk_f32_fp8_sdwa v[220:221], v115 src0_sel:WORD_1
	v_pk_fma_f32 v[210:211], v[178:179], v[218:219], v[210:211] op_sel_hi:[0,1,1]
	v_pk_fma_f32 v[212:213], v[178:179], v[220:221], v[212:213] op_sel_hi:[0,1,1]
	s_waitcnt vmcnt(26)
	v_cvt_pk_f32_fp8_e32 v[214:215], v116
	v_cvt_pk_f32_fp8_sdwa v[216:217], v116 src0_sel:WORD_1
	v_pk_fma_f32 v[198:199], v[178:179], v[214:215], v[198:199] op_sel:[1,0,0]
	v_pk_fma_f32 v[200:201], v[178:179], v[216:217], v[200:201] op_sel:[1,0,0]
	v_cvt_pk_f32_fp8_e32 v[218:219], v117
	v_cvt_pk_f32_fp8_sdwa v[220:221], v117 src0_sel:WORD_1
	v_pk_fma_f32 v[202:203], v[178:179], v[218:219], v[202:203] op_sel:[1,0,0]
	v_pk_fma_f32 v[204:205], v[178:179], v[220:221], v[204:205] op_sel:[1,0,0]
	v_cvt_pk_f32_fp8_e32 v[214:215], v118
	v_cvt_pk_f32_fp8_sdwa v[216:217], v118 src0_sel:WORD_1
	v_pk_fma_f32 v[206:207], v[178:179], v[214:215], v[206:207] op_sel:[1,0,0]
	v_pk_fma_f32 v[208:209], v[178:179], v[216:217], v[208:209] op_sel:[1,0,0]
	v_cvt_pk_f32_fp8_e32 v[218:219], v119
	v_cvt_pk_f32_fp8_sdwa v[220:221], v119 src0_sel:WORD_1
	v_pk_fma_f32 v[210:211], v[178:179], v[218:219], v[210:211] op_sel:[1,0,0]
	v_pk_fma_f32 v[212:213], v[178:179], v[220:221], v[212:213] op_sel:[1,0,0]
	s_waitcnt lgkmcnt(0)
	v_lshl_add_u32 v174, v174, 8, v138
	v_lshl_add_u32 v175, v175, 8, v138
	v_lshl_add_u32 v176, v176, 8, v138
	v_lshl_add_u32 v177, v177, 8, v138
	buffer_load_dwordx4 v[96:99], v174, s[16:19], s26 offen
	buffer_load_dwordx4 v[100:103], v175, s[16:19], s26 offen
	buffer_load_dwordx4 v[104:107], v176, s[16:19], s26 offen
	buffer_load_dwordx4 v[108:111], v177, s[16:19], s26 offen
	s_waitcnt vmcnt(29)
; __device__ __forceinline__ unsigned cvt_pk_bf16(float lo, float hi) { unsigned r; asm volatile("v_cvt_pk_bf16_f32 %0, %1, %2" : "=v"(r) : "v"(lo), "v"(hi)); return r; }
; #define LAS __attribute__((address_space(3)))
; __device__ __forceinline__ void kv8_pv(const u32x4 (&buf)[8], f32x2v (&o2)[8], const LAS float* srow, int b) {
;     const LAS f32x4* p4 = (const LAS f32x4*)(srow + b * 8);
;     const f32x4 p0 = p4[0], p1 = p4[1];
;     const float p[8] = {p0.x, p0.y, p0.z, p0.w, p1.x, p1.y, p1.z, p1.w};
; #pragma unroll
;     for (int u = 0; u < 8; ++u) {
;         const u32x4 v = buf[u]; const f32x2v pp = {p[u], p[u]};
;         o2[0] = __builtin_elementwise_fma(pp, __builtin_amdgcn_cvt_pk_f32_fp8(v.x, false), o2[0]); o2[1] = __builtin_elementwise_fma(pp, __builtin_amdgcn_cvt_pk_f32_fp8(v.x, true), o2[1]);
;         o2[2] = __builtin_elementwise_fma(pp, __builtin_amdgcn_cvt_pk_f32_fp8(v.y, false), o2[2]); o2[3] = __builtin_elementwise_fma(pp, __builtin_amdgcn_cvt_pk_f32_fp8(v.y, true), o2[3]);
;         o2[4] = __builtin_elementwise_fma(pp, __builtin_amdgcn_cvt_pk_f32_fp8(v.z, false), o2[4]); o2[5] = __builtin_elementwise_fma(pp, __builtin_amdgcn_cvt_pk_f32_fp8(v.z, true), o2[5]);
;         o2[6] = __builtin_elementwise_fma(pp, __builtin_amdgcn_cvt_pk_f32_fp8(v.w, false), o2[6]); o2[7] = __builtin_elementwise_fma(pp, __builtin_amdgcn_cvt_pk_f32_fp8(v.w, true), o2[7]);
;     }
; __device__ __forceinline__ void attn_query8(const unsigned char* __restrict__ KV8, const bf16_t* __restrict__ Z, const int* __restrict__ SEL, bf16_t* __restrict__ YMIX, int t, LAS float* sbuf  ) {
;     ...
;     for (int b = 0; b < nb; b += 3) {
;         kv8_issue(C, rs, lvo, 1024, iv, CLAMPB(b + 2));
;         kv8_pv(A, o, srow, b);
;         kv8_issue(A, rs, lvo, 1024, iv, CLAMPB(b + 3));
;         if (b + 1 < nb) kv8_pv(B, o, srow, b + 1);
;         kv8_issue(B, rs, lvo, 1024, iv, CLAMPB(b + 4));
;         if (b + 2 < nb) kv8_pv(C, o, srow, b + 2);
;     }
;     ...
;     u32x4 o0, o1;
;     o0.x = cvt_pk_bf16(o[0].x, o[0].y); o0.y = cvt_pk_bf16(o[1].x, o[1].y); o0.z = cvt_pk_bf16(o[2].x, o[2].y); o0.w = cvt_pk_bf16(o[3].x, o[3].y);
;     o1.x = cvt_pk_bf16(o[4].x, o[4].y); o1.y = cvt_pk_bf16(o[5].x, o[5].y); o1.z = cvt_pk_bf16(o[6].x, o[6].y); o1.w = cvt_pk_bf16(o[7].x, o[7].y);
;     u32x4* yp = (u32x4*)(YMIX + (size_t)t * D_ + 1024 + lane * 16);
;     yp[0] = o0; yp[1] = o1;
	v_cvt_pk_f32_fp8_e32 v[214:215], v120
	v_cvt_pk_f32_fp8_sdwa v[216:217], v120 src0_sel:WORD_1
	v_pk_fma_f32 v[198:199], v[180:181], v[214:215], v[198:199] op_sel_hi:[0,1,1]
	v_pk_fma_f32 v[200:201], v[180:181], v[216:217], v[200:201] op_sel_hi:[0,1,1]
	v_cvt_pk_f32_fp8_e32 v[218:219], v121
	v_cvt_pk_f32_fp8_sdwa v[220:221], v121 src0_sel:WORD_1
	v_pk_fma_f32 v[202:203], v[180:181], v[218:219], v[202:203] op_sel_hi:[0,1,1]
	v_pk_fma_f32 v[204:205], v[180:181], v[220:221], v[204:205] op_sel_hi:[0,1,1]
	v_cvt_pk_f32_fp8_e32 v[214:215], v122
	v_cvt_pk_f32_fp8_sdwa v[216:217], v122 src0_sel:WORD_1
	v_pk_fma_f32 v[206:207], v[180:181], v[214:215], v[206:207] op_sel_hi:[0,1,1]
	v_pk_fma_f32 v[208:209], v[180:181], v[216:217], v[208:209] op_sel_hi:[0,1,1]
	v_cvt_pk_f32_fp8_e32 v[218:219], v123
	v_cvt_pk_f32_fp8_sdwa v[220:221], v123 src0_sel:WORD_1
	v_pk_fma_f32 v[210:211], v[180:181], v[218:219], v[210:211] op_sel_hi:[0,1,1]
	v_pk_fma_f32 v[212:213], v[180:181], v[220:221], v[212:213] op_sel_hi:[0,1,1]
	s_waitcnt vmcnt(28)
	v_cvt_pk_f32_fp8_e32 v[214:215], v124
	v_cvt_pk_f32_fp8_sdwa v[216:217], v124 src0_sel:WORD_1
	v_pk_fma_f32 v[198:199], v[180:181], v[214:215], v[198:199] op_sel:[1,0,0]
	v_pk_fma_f32 v[200:201], v[180:181], v[216:217], v[200:201] op_sel:[1,0,0]
	v_cvt_pk_f32_fp8_e32 v[218:219], v125
	v_cvt_pk_f32_fp8_sdwa v[220:221], v125 src0_sel:WORD_1
	v_pk_fma_f32 v[202:203], v[180:181], v[218:219], v[202:203] op_sel:[1,0,0]
	v_pk_fma_f32 v[204:205], v[180:181], v[220:221], v[204:205] op_sel:[1,0,0]
	v_cvt_pk_f32_fp8_e32 v[214:215], v126
	v_cvt_pk_f32_fp8_sdwa v[216:217], v126 src0_sel:WORD_1
	v_pk_fma_f32 v[206:207], v[180:181], v[214:215], v[206:207] op_sel:[1,0,0]
	v_pk_fma_f32 v[208:209], v[180:181], v[216:217], v[208:209] op_sel:[1,0,0]
	v_cvt_pk_f32_fp8_e32 v[218:219], v127
	v_cvt_pk_f32_fp8_sdwa v[220:221], v127 src0_sel:WORD_1
	v_pk_fma_f32 v[210:211], v[180:181], v[218:219], v[210:211] op_sel:[1,0,0]
	v_pk_fma_f32 v[212:213], v[180:181], v[220:221], v[212:213] op_sel:[1,0,0]
	ds_read_b128 v[178:181], v139 offset:112
	v_add_f32_dpp v198, v198, v198 row_ror:8 row_mask:0xf bank_mask:0x3
	v_add_f32_dpp v199, v199, v199 row_ror:8 row_mask:0xf bank_mask:0x3
	v_add_f32_dpp v200, v200, v200 row_ror:8 row_mask:0xf bank_mask:0x3
	v_add_f32_dpp v201, v201, v201 row_ror:8 row_mask:0xf bank_mask:0x3
	v_add_f32_dpp v202, v202, v202 row_ror:8 row_mask:0xf bank_mask:0x3
	v_add_f32_dpp v203, v203, v203 row_ror:8 row_mask:0xf bank_mask:0x3
	v_add_f32_dpp v204, v204, v204 row_ror:8 row_mask:0xf bank_mask:0x3
	v_add_f32_dpp v205, v205, v205 row_ror:8 row_mask:0xf bank_mask:0x3
	v_add_f32_dpp v206, v206, v206 row_ror:8 row_mask:0xf bank_mask:0xc
	v_add_f32_dpp v207, v207, v207 row_ror:8 row_mask:0xf bank_mask:0xc
	v_add_f32_dpp v208, v208, v208 row_ror:8 row_mask:0xf bank_mask:0xc
	v_add_f32_dpp v209, v209, v209 row_ror:8 row_mask:0xf bank_mask:0xc
	v_add_f32_dpp v210, v210, v210 row_ror:8 row_mask:0xf bank_mask:0xc
	v_add_f32_dpp v211, v211, v211 row_ror:8 row_mask:0xf bank_mask:0xc
	v_add_f32_dpp v212, v212, v212 row_ror:8 row_mask:0xf bank_mask:0xc
	v_add_f32_dpp v213, v213, v213 row_ror:8 row_mask:0xf bank_mask:0xc
	v_mov_b32_dpp v198, v206 quad_perm:[0,1,2,3] row_mask:0xf bank_mask:0xc
	v_mov_b32_dpp v199, v207 quad_perm:[0,1,2,3] row_mask:0xf bank_mask:0xc
	v_mov_b32_dpp v200, v208 quad_perm:[0,1,2,3] row_mask:0xf bank_mask:0xc
	v_mov_b32_dpp v201, v209 quad_perm:[0,1,2,3] row_mask:0xf bank_mask:0xc
	v_mov_b32_dpp v202, v210 quad_perm:[0,1,2,3] row_mask:0xf bank_mask:0xc
	v_mov_b32_dpp v203, v211 quad_perm:[0,1,2,3] row_mask:0xf bank_mask:0xc
	v_mov_b32_dpp v204, v212 quad_perm:[0,1,2,3] row_mask:0xf bank_mask:0xc
	v_mov_b32_dpp v205, v213 quad_perm:[0,1,2,3] row_mask:0xf bank_mask:0xc
	s_waitcnt lgkmcnt(0)
	v_lshl_add_u32 v178, v178, 8, v138
	v_lshl_add_u32 v179, v179, 8, v138
	v_lshl_add_u32 v180, v180, 8, v138
	v_lshl_add_u32 v181, v181, 8, v138
	buffer_load_dwordx4 v[112:115], v178, s[16:19], s26 offen
	buffer_load_dwordx4 v[116:119], v179, s[16:19], s26 offen
	buffer_load_dwordx4 v[120:123], v180, s[16:19], s26 offen
	buffer_load_dwordx4 v[124:127], v181, s[16:19], s26 offen
	s_nop 1
	v_permlane16_swap_b32_e32 v198, v202
	v_add_f32_e32 v198, v198, v202
	v_permlane16_swap_b32_e32 v199, v203
	v_add_f32_e32 v199, v199, v203
	v_permlane16_swap_b32_e32 v200, v204
	v_add_f32_e32 v200, v200, v204
	v_permlane16_swap_b32_e32 v201, v205
	v_add_f32_e32 v201, v201, v205
	s_nop 0
	v_permlane32_swap_b32_e32 v198, v200
	v_add_f32_e32 v198, v198, v200
	v_permlane32_swap_b32_e32 v199, v201
	v_add_f32_e32 v199, v199, v201
	s_ashr_i32 s81, s80, 31
	s_lshl_b64 s[10:11], s[80:81], 12
	s_add_u32 s10, s14, s10
	s_addc_u32 s11, s15, s11
	v_mul_f32_e32 v198, v198, v149
	v_mul_f32_e32 v199, v199, v149
	v_cvt_pk_bf16_f32 v214, v198, v199
	global_store_dword v238, v214, s[10:11] offset:2048
	s_addk_i32 s80, 0x100
	s_cmpk_gt_i32 s80, 0x3fff
	s_cbranch_scc0 .Latt_unit
	s_waitcnt vmcnt(0)
